# far-tile bias constant kept in a register, NSA window pass accumulates in place, bias1 dot products moved to the workgroups with the fewest weight tiles
# baseline (speedup 1.0000x reference)
; __device__ __forceinline__ float wave_sum(float v) { v += __shfl_xor(v, 1); v += __shfl_xor(v, 2); v += __shfl_xor(v, 4); v += __shfl_xor(v, 8); v += __shfl_xor(v, 16); v += __shfl_xor(v, 32); return v; }
; #define INP(k) ({ int k_ = (k); LAUNDER_S(k_); (const float*)(const GAS float*)P.in[k_]; })
; __global__ void __launch_bounds__(512, 2) hybrid_fwd(Params P) {
;     ...
;             if (gwave < 512) { const int kv = gwave >> 8, j = gwave & 255; const float* pp = INP(8) + (size_t)L * 2 * 2048 + kv * 2048; const float* ww = cw1 + (size_t)kv * 2048 * 256 + j; float a = 0.f;
; #pragma unroll 8
;                 for (int i = lane; i < 2048; i += 64) a = fmaf(pp[i], ww[(size_t)i * 256], a);
;                 a = wave_sum(a);
;                 if (lane == 0) ((float*)(ws + WS_SMALL))[kv * 256 + j] = a; }
.LBB0_391:
	s_addk_i32 s4, 0x200
	s_and_b32 s4, s4, 0x7ff
	s_cmpk_gt_i32 s4, 0x1ff
	s_cbranch_scc1 .LBB0_397
	s_mov_b32 s18, 8
	s_ashr_i32 s19, s18, 31
	s_ashr_i32 s16, s4, 8
	s_and_b32 s5, s4, 0xff
	s_lshl_b64 s[18:19], s[18:19], 3
	s_add_u32 s18, s0, s18
	s_addc_u32 s19, s1, s19
	s_lshl_b32 s22, s16, 11
	s_ashr_i32 s17, s16, 31
	s_lshl_b64 s[20:21], s[10:11], 14
	s_ashr_i32 s23, s22, 31
	s_lshl_b64 s[16:17], s[16:17], 21
	s_add_u32 s11, s14, s16
	s_addc_u32 s14, s15, s17
	s_lshl_b32 s5, s5, 2
	s_add_u32 s5, s6, s5
	s_addc_u32 s7, s7, 0
	s_add_u32 s6, s5, s11
	s_load_dwordx2 s[18:19], s[18:19], 0x0
	v_lshlrev_b32_e32 v80, 10, v33
	s_addc_u32 s7, s7, s14
	s_waitcnt vmcnt(1)
	v_lshl_add_u64 v[0:1], s[6:7], 0, v[80:81]
	s_mov_b64 s[6:7], 0x70000
	v_lshl_add_u64 v[0:1], v[0:1], 0, s[6:7]
	s_lshl_b64 s[6:7], s[22:23], 2
	s_add_u32 s5, s20, s6
	s_addc_u32 s7, s21, s7
	s_waitcnt lgkmcnt(0)
	s_add_u32 s6, s18, s5
	v_lshlrev_b32_e32 v80, 2, v33
	s_addc_u32 s7, s19, s7
	v_lshl_add_u64 v[2:3], s[6:7], 0, v[80:81]
	s_mov_b64 s[6:7], 0x700
	v_or_b32_e32 v4, 0xfffffe00, v33
	v_lshl_add_u64 v[2:3], v[2:3], 0, s[6:7]
	v_mov_b32_e32 v5, 0
	s_mov_b64 s[6:7], 0

;     __host__ __device__ bool next(int i, Unit& u) const {
;         const long L = (long)i * G + c; if (L >= nwg) return false;
;         int wgid = (int)L; { const int q = nwg / NXCD, r = nwg % NXCD, xcd = wgid % NXCD, off = wgid / NXCD; wgid = (xcd < r ? xcd * (q + 1) : r * (q + 1) + (xcd - r) * q) + off; }
;         const int nig = WGM * nN, gid = wgid / nig, fm = gid * WGM, gsz = (nM - fm) < WGM ? (nM - fm) : WGM;
;         u.pm = fm + ((wgid % nig) % gsz); u.pn = (wgid % nig) / gsz; return true;
;     }
; template <class Epi, class Sched, bool ALIGN_EPI = false, bool SP2 = false>
; __device__ __forceinline__ void gemm_phase(PG8_LAS unsigned char* lds, const Gemm g, const Sched& S, const Epi& E, int tid_in) {
;     ...
;     Unit cur, nxt; int ui = 0;
;     if (!S.next(0, cur)) return;
.LBB0_423:
	s_nop 0
	s_nop 0
	s_nop 0
	s_nop 0
	s_nop 0
	s_nop 0
	s_nop 0
	s_nop 0
	s_nop 0
	s_nop 0
	s_nop 0
	s_nop 0
	s_nop 0
	s_or_b64 exec, exec, s[4:5]
	s_mov_b32 s10, s20
	s_mov_b64 s[4:5], s[58:59]
	s_mov_b32 s52, s69
	s_mov_b32 s53, s2
	s_barrier
	v_mov_b32_e32 v8, v146
	s_cmpk_lt_i32 s53, 0xc00
	s_cselect_b64 s[6:7], -1, 0
	s_cmpk_gt_i32 s53, 0xbff
	v_readfirstlane_b32 s20, v8
	s_cbranch_scc1 .LBB0_425
	s_ashr_i32 s8, s53, 31
	s_lshr_b32 s8, s8, 29
	s_add_i32 s8, s53, s8
	s_ashr_i32 s9, s8, 3
	s_and_b32 s8, s8, -8
	s_sub_i32 s8, s53, s8
	s_cmp_lt_i32 s8, 0
	s_movk_i32 s11, 0x181
	s_cselect_b32 s11, s11, 0x180
	s_mul_i32 s8, s8, s11
	s_add_i32 s8, s8, s9
	s_mul_hi_i32 s9, s8, 0x2aaaaaab
	s_lshr_b32 s11, s9, 31
	s_ashr_i32 s9, s9, 5
	s_add_i32 s9, s9, s11
	s_lshl_b32 s11, s9, 3
	s_mulk_i32 s9, 0xc0
	s_sub_i32 s8, s8, s9
	s_bfe_u32 s9, s8, 0x3001c
	s_add_i32 s9, s8, s9
	s_sext_i32_i16 s12, s9
	s_and_b32 s9, s9, 0xfff8
	s_sub_i32 s8, s8, s9
	s_sext_i32_i16 s8, s8
	s_add_i32 s38, s11, s8
	s_ashr_i32 s36, s12, 3

; #define LAS __attribute__((address_space(3)))
; #define MOBA_NEXT(k_, out_) do { int kk_ = (k_) + 64; while (kk_ < q0 && !((uni >> (kk_ >> 8)) & 1u)) kk_ = (kk_ | 255) + 1; (out_) = kk_; } while (0)
; __device__ __forceinline__ void tile_soft_far(LAS const unsigned char* ks, LAS const unsigned char* vs, const bf16x8 (&qf)[4], f32x16 (&ot)[2], float& lsum, bool lane_valid, LAS const float* bt, int r, int h) {
;     const float init = lane_valid ? bt[BT_FAR] : -3.0e38f;
;     const int pr = (r & 0x13) | ((r & 4) << 1) | ((r & 8) >> 1);
;     LAS const unsigned char* kp = ks + pr * 144 + h * 16; LAS const unsigned char* vp = vs + r * 144 + h * 16;
; __device__ __forceinline__ void moba_unit(LAS unsigned char* lds, const unsigned char* hb, const float* kmean, bf16_t* omix, int b, int hd, int blk, int tid) {
;     ...
;     bf16x8 qf[4]; load_q(Qb + (size_t)(32 * w + r) * 64, h, qf);
;     f32x16 ot[2]; zero_ot(ot); float lsum = 0.f;
;     const int kend = q0 + 256;
;     ...
;     int key0, knext, knext2; MOBA_NEXT(-64, key0); MOBA_NEXT(key0, knext);
;     u32x4 rkA_, rvA_, rkB_, rvB_;
;     stage_ld(K, Vt, SEQ, key0, tid, rkA_, rvA_); stage_st(lds, 0, tid, rkA_, rvA_);
;     if (knext < kend) stage_ld(K, Vt, SEQ, knext, tid, rkA_, rvA_);
;     __syncthreads();
;     int buf = 0;
;     while (key0 < kend) {
.LBB0_896:
	s_and_b32 s17, s4, 3
	v_add_u32_e32 v35, s76, v108
	v_mov_b32_e32 v15, 0
	v_or_b32_e32 v136, v35, v34
	s_cmp_ge_i32 s16, s23
	v_mov_b32_e32 v14, v15
	v_mov_b32_e32 v13, v15
	v_mov_b32_e32 v12, v15
	v_mov_b32_e32 v11, v15
	v_mov_b32_e32 v10, v15
	v_mov_b32_e32 v9, v15
	v_mov_b32_e32 v8, v15
	v_mov_b32_e32 v7, v15
	v_mov_b32_e32 v6, v15
	v_mov_b32_e32 v5, v15
	v_mov_b32_e32 v4, v15
	v_mov_b32_e32 v3, v15
	v_mov_b32_e32 v2, v15
	v_mov_b32_e32 v1, v15
	v_mov_b32_e32 v0, v15
	v_mov_b32_e32 v31, v15
	v_mov_b32_e32 v30, v15
	v_mov_b32_e32 v29, v15
	v_mov_b32_e32 v28, v15
	v_mov_b32_e32 v27, v15
	v_mov_b32_e32 v26, v15
	v_mov_b32_e32 v25, v15
	v_mov_b32_e32 v24, v15
	v_mov_b32_e32 v23, v15
	v_mov_b32_e32 v22, v15
	v_mov_b32_e32 v21, v15
	v_mov_b32_e32 v20, v15
	v_mov_b32_e32 v19, v15
	v_mov_b32_e32 v18, v15
	v_mov_b32_e32 v17, v15
	v_mov_b32_e32 v16, v15
	v_mov_b32_e32 v144, v15
	s_waitcnt lgkmcnt(0)
	s_barrier
	s_cbranch_scc1 .LBB0_1049
	v_lshlrev_b32_e32 v1, 1, v34
	v_lshrrev_b32_e32 v2, 1, v130
	v_and_b32_e32 v0, 19, v130
	v_and_b32_e32 v1, 8, v1
	v_and_b32_e32 v2, 4, v2
	v_lshl_add_u64 v[140:141], s[6:7], 0, v[80:81]
	s_mul_i32 s6, s17, 0x480
	v_or3_b32 v0, v2, v0, v1
	v_mov_b32_e32 v144, 0
	v_lshl_add_u64 v[142:143], v[32:33], 0, v[80:81]
	s_add_i32 s24, s6, 0x100
	v_mov_b32_e32 v235, s24
	ds_read_b32 v235, v235 offset:38012
	s_waitcnt lgkmcnt(0)
	v_or_b32_e32 v80, 31, v35
	v_subrev_u32_e32 v135, 63, v35
	v_mul_u32_u24_e32 v137, 0x90, v0
	v_mul_u32_u24_e32 v139, 0x90, v34
	s_mov_b32 s25, 0
	v_mov_b32_e32 v16, 0
	v_mov_b32_e32 v17, v144
	v_mov_b32_e32 v18, v144
	v_mov_b32_e32 v19, v144
	v_mov_b32_e32 v20, v144
	v_mov_b32_e32 v21, v144
	v_mov_b32_e32 v22, v144
	v_mov_b32_e32 v23, v144
	v_mov_b32_e32 v24, v144
	v_mov_b32_e32 v25, v144
	v_mov_b32_e32 v26, v144
	v_mov_b32_e32 v27, v144
	v_mov_b32_e32 v28, v144
	v_mov_b32_e32 v29, v144
	v_mov_b32_e32 v30, v144
	v_mov_b32_e32 v31, v144
	v_mov_b32_e32 v0, 0
	v_mov_b32_e32 v1, v144
	v_mov_b32_e32 v2, v144
	v_mov_b32_e32 v3, v144
	v_mov_b32_e32 v4, v144
	v_mov_b32_e32 v5, v144
	v_mov_b32_e32 v6, v144
	v_mov_b32_e32 v7, v144
	v_mov_b32_e32 v8, v144
	v_mov_b32_e32 v9, v144
	v_mov_b32_e32 v10, v144
	v_mov_b32_e32 v11, v144
	v_mov_b32_e32 v12, v144
	v_mov_b32_e32 v13, v144
	v_mov_b32_e32 v14, v144
	v_mov_b32_e32 v15, v144
	s_mov_b32 s26, s8
	s_add_i32 s8, s8, 64
	s_cmp_ge_i32 s8, s76
	s_cbranch_scc0 .LBB0_908

; #define LAS __attribute__((address_space(3)))
; #define MFMA32(a, b, c) __builtin_amdgcn_mfma_f32_32x32x16_bf16((a), (b), (c), 0, 0, 0)
; __device__ __forceinline__ void tile_soft_far(LAS const unsigned char* ks, LAS const unsigned char* vs, const bf16x8 (&qf)[4], f32x16 (&ot)[2], float& lsum, bool lane_valid, LAS const float* bt, int r, int h) {
;     const float init = lane_valid ? bt[BT_FAR] : -3.0e38f;
;     const int pr = (r & 0x13) | ((r & 4) << 1) | ((r & 8) >> 1);
;     LAS const unsigned char* kp = ks + pr * 144 + h * 16; LAS const unsigned char* vp = vs + r * 144 + h * 16;
;     bf16x8 k0[4], k1[4], v0[2][2], v1[2][2];
; #pragma unroll
;     for (int kk = 0; kk < 4; ++kk) { k0[kk] = *(LAS const bf16x8*)(kp + kk * 32); k1[kk] = *(LAS const bf16x8*)(kp + 32 * 144 + kk * 32); }
;     __builtin_amdgcn_sched_barrier(0);
;     f32x16 s0, s1;
; #pragma unroll
;     for (int i = 0; i < 16; ++i) { s0[i] = init; s1[i] = init; }
; #pragma unroll
;     for (int kk = 0; kk < 4; ++kk) s0 = MFMA32(k0[kk], qf[kk], s0);
; #pragma unroll
;     for (int mt = 0; mt < 2; ++mt)
; #pragma unroll
;         for (int j = 0; j < 2; ++j) { v0[mt][j] = *(LAS const bf16x8*)(vp + 32 * mt * 144 + 32 * j); v1[mt][j] = *(LAS const bf16x8*)(vp + 32 * mt * 144 + 64 + 32 * j); }
;     __builtin_amdgcn_sched_barrier(0);
;     s1 = MFMA32(k1[0], qf[0], s1); SOFT4(s0, 0);  __builtin_amdgcn_sched_barrier(0);
;     s1 = MFMA32(k1[1], qf[1], s1); SOFT4(s0, 4);  __builtin_amdgcn_sched_barrier(0);
;     s1 = MFMA32(k1[2], qf[2], s1); SOFT4(s0, 8);  __builtin_amdgcn_sched_barrier(0);
;     s1 = MFMA32(k1[3], qf[3], s1); SOFT4(s0, 12); __builtin_amdgcn_sched_barrier(0);
;     const bf16x8 pa = pack_p(s0, 0);
;     ot[0] = MFMA32(v0[0][0], pa, ot[0]); SOFT4(s1, 0);  __builtin_amdgcn_sched_barrier(0);
;     ot[1] = MFMA32(v0[1][0], pa, ot[1]); SOFT4(s1, 4);  const bf16x8 pb = pack_p(s0, 1); __builtin_amdgcn_sched_barrier(0);
;     ot[0] = MFMA32(v0[0][1], pb, ot[0]); SOFT4(s1, 8);  __builtin_amdgcn_sched_barrier(0);
;     ot[1] = MFMA32(v0[1][1], pb, ot[1]); SOFT4(s1, 12); __builtin_amdgcn_sched_barrier(0);
; #pragma unroll
;     for (int j = 0; j < 2; ++j) { const bf16x8 pf = pack_p(s1, j); ot[0] = MFMA32(v1[0][j], pf, ot[0]); ot[1] = MFMA32(v1[1][j], pf, ot[1]); }
; }
.LBB0_912:
	s_mul_i32 s9, s25, 0x4800
	v_subrev_u32_e32 v32, s16, v135
	s_addk_i32 s9, 0x100
	s_or_b64 vcc, s[18:19], s[6:7]
	v_cmp_lt_i32_e64 s[6:7], s65, v32
	s_and_saveexec_b64 s[18:19], s[6:7]
	s_xor_b64 s[6:7], exec, s[18:19]
	s_cbranch_execz .LBB0_916
	v_mov_b32_e32 v32, 0xff61b1e6
	v_cndmask_b32_e32 v32, v32, v235, vcc
	v_add3_u32 v33, s9, v137, v134
	ds_read_b128 v[98:101], v33
	ds_read_b128 v[102:105], v33 offset:32
	ds_read_b128 v[114:117], v33 offset:4608
	ds_read_b128 v[118:121], v33 offset:4640
	ds_read_b128 v[106:109], v33 offset:64
	ds_read_b128 v[122:125], v33 offset:96
	ds_read_b128 v[126:129], v33 offset:4672
	ds_read_b128 v[152:155], v33 offset:4704
	s_waitcnt lgkmcnt(8)
	v_mov_b32_e32 v33, v32
	v_mov_b32_e32 v34, v32
	v_mov_b32_e32 v35, v32
	v_mov_b32_e32 v36, v32
	v_mov_b32_e32 v37, v32
	v_mov_b32_e32 v38, v32
	v_mov_b32_e32 v39, v32
	v_mov_b32_e32 v40, v32
	v_mov_b32_e32 v41, v32
	v_mov_b32_e32 v42, v32
	v_mov_b32_e32 v43, v32
	v_mov_b32_e32 v44, v32
	v_mov_b32_e32 v45, v32
	v_mov_b32_e32 v46, v32
	v_mov_b32_e32 v47, v32
	s_waitcnt lgkmcnt(7)
	s_nop 0
	v_mfma_f32_32x32x16_bf16 v[48:63], v[98:101], v[64:67], v[32:47]
	s_waitcnt lgkmcnt(6)
	v_mfma_f32_32x32x16_bf16 v[48:63], v[102:105], v[68:71], v[48:63]
	v_add3_u32 v102, s9, v139, v134
	s_waitcnt lgkmcnt(3)
	v_mfma_f32_32x32x16_bf16 v[48:63], v[106:109], v[72:75], v[48:63]
	ds_read_b128 v[156:159], v102 offset:9216
	ds_read_b128 v[160:163], v102 offset:9248
	ds_read_b128 v[106:109], v102 offset:9280
	ds_read_b128 v[98:101], v102 offset:9312
	ds_read_b128 v[170:173], v102 offset:13824
	ds_read_b128 v[174:177], v102 offset:13856
	ds_read_b128 v[110:113], v102 offset:13888
	ds_read_b128 v[102:105], v102 offset:13920
	s_waitcnt lgkmcnt(10)
	v_mfma_f32_32x32x16_bf16 v[48:63], v[122:125], v[76:79], v[48:63]
	s_nop 11
	v_exp_f32_e32 v48, v48
	v_exp_f32_e32 v49, v49
	v_exp_f32_e32 v50, v50
	v_exp_f32_e32 v51, v51
	v_add_f32_e32 v122, v144, v48
	v_add_f32_e32 v122, v49, v122
	v_add_f32_e32 v122, v50, v122
	v_add_f32_e32 v122, v51, v122
	v_exp_f32_e32 v52, v52
	v_exp_f32_e32 v53, v53
	v_exp_f32_e32 v54, v54
	v_exp_f32_e32 v55, v55
	v_add_f32_e32 v122, v52, v122
	v_add_f32_e32 v122, v53, v122
	v_add_f32_e32 v122, v54, v122
	v_add_f32_e32 v122, v55, v122
	v_mfma_f32_32x32x16_bf16 v[32:47], v[114:117], v[64:67], v[32:47]
	v_exp_f32_e32 v56, v56
	v_exp_f32_e32 v57, v57
	v_exp_f32_e32 v58, v58
	v_exp_f32_e32 v59, v59
	v_add_f32_e32 v114, v56, v122
	v_add_f32_e32 v114, v57, v114
	v_add_f32_e32 v114, v58, v114
	v_add_f32_e32 v114, v59, v114
	v_mfma_f32_32x32x16_bf16 v[32:47], v[118:121], v[68:71], v[32:47]
	s_waitcnt lgkmcnt(9)
	v_mfma_f32_32x32x16_bf16 v[32:47], v[126:129], v[72:75], v[32:47]
	v_exp_f32_e32 v60, v60
	v_exp_f32_e32 v61, v61
	v_exp_f32_e32 v62, v62
	v_exp_f32_e32 v63, v63
	v_add_f32_e32 v114, v60, v114
	v_add_f32_e32 v114, v61, v114
	v_add_f32_e32 v114, v62, v114
	v_add_f32_e32 v114, v63, v114
	s_waitcnt lgkmcnt(8)
	v_mfma_f32_32x32x16_bf16 v[32:47], v[152:155], v[76:79], v[32:47]
	v_cvt_pk_bf16_f32 v48, v48, v49
	v_cvt_pk_bf16_f32 v49, v50, v51
	v_cvt_pk_bf16_f32 v50, v52, v53
	v_cvt_pk_bf16_f32 v51, v54, v55
	s_nop 7
	v_exp_f32_e32 v52, v32
	v_exp_f32_e32 v53, v33
	s_waitcnt lgkmcnt(7)
	v_mfma_f32_32x32x16_bf16 v[16:31], v[156:159], v[48:51], v[16:31]
	v_exp_f32_e32 v54, v34
	v_exp_f32_e32 v55, v35
	v_add_f32_e32 v32, v52, v114
	v_add_f32_e32 v32, v53, v32
	v_add_f32_e32 v32, v54, v32
	v_add_f32_e32 v32, v55, v32
	s_waitcnt lgkmcnt(3)
	v_mfma_f32_32x32x16_bf16 v[0:15], v[170:173], v[48:51], v[0:15]
	v_exp_f32_e32 v36, v36
	v_exp_f32_e32 v37, v37
	v_exp_f32_e32 v38, v38
	v_exp_f32_e32 v39, v39
	v_add_f32_e32 v32, v36, v32
	v_add_f32_e32 v32, v37, v32
	v_add_f32_e32 v32, v38, v32
	v_add_f32_e32 v48, v39, v32
	v_cvt_pk_bf16_f32 v32, v56, v57
	v_cvt_pk_bf16_f32 v33, v58, v59
	v_cvt_pk_bf16_f32 v34, v60, v61
	v_cvt_pk_bf16_f32 v35, v62, v63
	s_nop 1
	v_mfma_f32_32x32x16_bf16 v[16:31], v[160:163], v[32:35], v[16:31]
	v_exp_f32_e32 v40, v40
	v_exp_f32_e32 v41, v41
	v_exp_f32_e32 v42, v42
	v_exp_f32_e32 v43, v43
	v_add_f32_e32 v48, v40, v48
	v_add_f32_e32 v48, v41, v48
	v_add_f32_e32 v48, v42, v48
	v_add_f32_e32 v48, v43, v48
	s_waitcnt lgkmcnt(2)
	v_mfma_f32_32x32x16_bf16 v[0:15], v[174:177], v[32:35], v[0:15]
	v_exp_f32_e32 v44, v44
	v_exp_f32_e32 v45, v45
	v_exp_f32_e32 v46, v46
	v_exp_f32_e32 v47, v47
	v_add_f32_e32 v32, v44, v48
	v_add_f32_e32 v32, v45, v32
	v_add_f32_e32 v32, v46, v32
	v_add_f32_e32 v144, v47, v32
	v_cvt_pk_bf16_f32 v32, v52, v53
	v_cvt_pk_bf16_f32 v33, v54, v55
	v_cvt_pk_bf16_f32 v34, v36, v37
	v_cvt_pk_bf16_f32 v35, v38, v39
	s_nop 1
	v_mfma_f32_32x32x16_bf16 v[16:31], v[106:109], v[32:35], v[16:31]
	s_waitcnt lgkmcnt(1)
	v_mfma_f32_32x32x16_bf16 v[0:15], v[110:113], v[32:35], v[0:15]
	v_cvt_pk_bf16_f32 v32, v40, v41
	v_cvt_pk_bf16_f32 v33, v42, v43
	v_cvt_pk_bf16_f32 v34, v44, v45
	v_cvt_pk_bf16_f32 v35, v46, v47
	s_nop 1
	v_mfma_f32_32x32x16_bf16 v[16:31], v[98:101], v[32:35], v[16:31]
	s_waitcnt lgkmcnt(0)
	v_mfma_f32_32x32x16_bf16 v[0:15], v[102:105], v[32:35], v[0:15]

; __device__ __forceinline__ void nsa_unit(LAS unsigned char* lds, const unsigned char* hb, const bf16_t* kc, const bf16_t* vct, const float* nsg, bf16_t* omix, int b, int g, int c, int tid) {
;     ...
;     const unsigned sel0 = selm[ql * 4], sel1 = selm[ql * 4 + 1], sel2 = selm[ql * 4 + 2], sel3 = selm[ql * 4 + 3];
;     { const bf16_t* Ks = (const bf16_t*)(hb + HB_KS * MiB) + (size_t)bg * SEQ * 64; const bf16_t* Vs = (const bf16_t*)(hb + HB_VST * MiB) + (size_t)bg * 64 * SEQ;
;         zero_ot(ot); lsum = 0.f;
;         TILE_LOOP(Ks, Vs, SEQ, 0, c + 1, {
.LBB0_1016:
	ds_read_b32 v234, v211 offset:42620
	s_lshl_b32 s76, s16, 20
	s_add_u32 s6, s26, s76
	v_readlane_b32 s7, v255, 24
	v_lshl_add_u32 v0, v131, 4, v165
	s_addc_u32 s7, s7, 0
	v_readlane_b32 s8, v255, 25
	s_waitcnt lgkmcnt(0)
	s_barrier
	ds_read_b128 v[98:101], v0 offset:50944
	s_add_u32 s8, s8, s76
	v_readlane_b32 s9, v255, 26
	v_lshl_add_u64 v[0:1], s[6:7], 0, v[114:115]
	v_mov_b32_e32 v135, v81
	s_addc_u32 s9, s9, 0
	v_lshl_add_u64 v[4:5], v[0:1], 0, v[134:135]
	v_lshlrev_b64 v[0:1], 14, v[136:137]
	v_lshl_add_u64 v[2:3], s[8:9], 0, v[0:1]
	v_lshl_add_u64 v[2:3], v[2:3], 0, v[134:135]
	s_waitcnt lgkmcnt(0)
	s_barrier
	global_load_dwordx4 v[102:105], v[4:5], off
	global_load_dwordx4 v[106:109], v[2:3], off
	s_cmpk_eq_i32 s15, 0x7f
	s_waitcnt vmcnt(1)
	ds_write_b128 v155, v[102:105]
	s_waitcnt vmcnt(0)
	ds_write_b128 v155, v[106:109] offset:9216
	s_cbranch_scc1 .LBB0_1018
	v_add_co_u32_e32 v4, vcc, 0x2000, v4
	s_nop 1
	v_addc_co_u32_e32 v5, vcc, 0, v5, vcc
	global_load_dwordx4 v[102:105], v[4:5], off
	global_load_dwordx4 v[106:109], v[2:3], off offset:128

; __device__ __forceinline__ void tile_soft_far(LAS const unsigned char* ks, LAS const unsigned char* vs, const bf16x8 (&qf)[4], f32x16 (&ot)[2], float& lsum, bool lane_valid, LAS const float* bt, int r, int h) {
;     const float init = lane_valid ? bt[BT_FAR] : -3.0e38f;
;     const int pr = (r & 0x13) | ((r & 4) << 1) | ((r & 8) >> 1);
;     LAS const unsigned char* kp = ks + pr * 144 + h * 16; LAS const unsigned char* vp = vs + r * 144 + h * 16;
;     bf16x8 k0[4], k1[4], v0[2][2], v1[2][2];
; #pragma unroll
;     for (int kk = 0; kk < 4; ++kk) { k0[kk] = *(LAS const bf16x8*)(kp + kk * 32); k1[kk] = *(LAS const bf16x8*)(kp + 32 * 144 + kk * 32); }
;     __builtin_amdgcn_sched_barrier(0);
;     f32x16 s0, s1;
; #pragma unroll
;     for (int i = 0; i < 16; ++i) { s0[i] = init; s1[i] = init; }
; #pragma unroll
;     for (int kk = 0; kk < 4; ++kk) s0 = MFMA32(k0[kk], qf[kk], s0);
; #pragma unroll
;     for (int mt = 0; mt < 2; ++mt)
; #pragma unroll
;         for (int j = 0; j < 2; ++j) { v0[mt][j] = *(LAS const bf16x8*)(vp + 32 * mt * 144 + 32 * j); v1[mt][j] = *(LAS const bf16x8*)(vp + 32 * mt * 144 + 64 + 32 * j); }
;     __builtin_amdgcn_sched_barrier(0);
;     s1 = MFMA32(k1[0], qf[0], s1); SOFT4(s0, 0);  __builtin_amdgcn_sched_barrier(0);
;     s1 = MFMA32(k1[1], qf[1], s1); SOFT4(s0, 4);  __builtin_amdgcn_sched_barrier(0);
;     s1 = MFMA32(k1[2], qf[2], s1); SOFT4(s0, 8);  __builtin_amdgcn_sched_barrier(0);
;     s1 = MFMA32(k1[3], qf[3], s1); SOFT4(s0, 12); __builtin_amdgcn_sched_barrier(0);
;     const bf16x8 pa = pack_p(s0, 0);
;     ot[0] = MFMA32(v0[0][0], pa, ot[0]); SOFT4(s1, 0);  __builtin_amdgcn_sched_barrier(0);
; __device__ __forceinline__ void nsa_unit(LAS unsigned char* lds, const unsigned char* hb, const bf16_t* kc, const bf16_t* vct, const float* nsg, bf16_t* omix, int b, int g, int c, int tid) {
;     ...
;         TILE_LOOP(Ks, Vs, SEQ, 0, c + 1, {
;             const int m = key0 >> 6; const unsigned sw = m < 32 ? sel0 : (m < 64 ? sel1 : (m < 96 ? sel2 : sel3));
;             const bool lane_valid = ((sw >> (m & 31)) & 1u) != 0u;
;             if (__ballot(lane_valid) != 0ull) { const int dist00 = t - (key0 + 8 * h);
;                 if ((c - m) < 3) tile_soft<1>(ks, vs, qf, ot, lsum, lane_valid, dist00, 0, bt, r, h);
;                 else tile_soft<0>(ks, vs, qf, ot, lsum, lane_valid, dist00, 0, bt, r, h); } });
.LBB0_1020:
	s_and_b32 s16, s15, 1
	s_cmpk_lt_u32 s13, 0x800
	s_cselect_b64 vcc, -1, 0
	s_cmpk_lt_u32 s13, 0x1000
	s_cselect_b64 s[6:7], -1, 0
	s_cmpk_lt_u32 s13, 0x1800
	s_cselect_b64 s[8:9], -1, 0
	v_cndmask_b32_e64 v32, v101, v100, s[8:9]
	v_cndmask_b32_e64 v32, v32, v99, s[6:7]
	v_cndmask_b32_e32 v32, v32, v98, vcc
	s_and_b32 s8, s15, 31
	v_lshrrev_b32_e32 v33, s15, v32
	v_and_b32_e32 v33, 1, v33
	v_bfe_u32 v32, v32, s8, 1
	v_cmp_eq_u32_e64 s[6:7], 1, v33
	v_cmp_ne_u32_e32 vcc, 0, v32
	s_cbranch_vccz .LBB0_1028
	s_mul_i32 s8, s16, 0x4800
	s_add_i32 s17, s8, 0x100
	s_cmp_le_i32 s15, s11
	s_mov_b64 s[8:9], -1
	s_cbranch_scc0 .LBB0_1025
	v_mov_b32_e32 v64, 0xff61b1e6
	v_cndmask_b32_e64 v64, v64, v234, s[6:7]
	v_add3_u32 v32, s17, v212, v154
	ds_read_b128 v[48:51], v32
	ds_read_b128 v[52:55], v32 offset:32
	ds_read_b128 v[56:59], v32 offset:4608
	ds_read_b128 v[60:63], v32 offset:4640
	ds_read_b128 v[118:121], v32 offset:64
	ds_read_b128 v[160:163], v32 offset:96
	ds_read_b128 v[170:173], v32 offset:4672
	ds_read_b128 v[174:177], v32 offset:4704
	s_waitcnt lgkmcnt(8)
	v_mov_b32_e32 v65, v64
	v_mov_b32_e32 v66, v64
	v_mov_b32_e32 v67, v64
	v_mov_b32_e32 v68, v64
	v_mov_b32_e32 v69, v64
	v_mov_b32_e32 v70, v64
	v_mov_b32_e32 v71, v64
	v_mov_b32_e32 v72, v64
	v_mov_b32_e32 v73, v64
	v_mov_b32_e32 v74, v64
	v_mov_b32_e32 v75, v64
	v_mov_b32_e32 v76, v64
	v_mov_b32_e32 v77, v64
	v_mov_b32_e32 v78, v64
	v_mov_b32_e32 v79, v64
	s_waitcnt lgkmcnt(7)
	s_nop 0
	v_mfma_f32_32x32x16_bf16 v[32:47], v[48:51], v[82:85], v[64:79]
	v_add3_u32 v48, s17, v213, v154
	s_waitcnt lgkmcnt(6)
	v_mfma_f32_32x32x16_bf16 v[32:47], v[52:55], v[86:89], v[32:47]
	s_waitcnt lgkmcnt(3)
	v_mfma_f32_32x32x16_bf16 v[32:47], v[118:121], v[90:93], v[32:47]
	ds_read_b128 v[218:221], v48 offset:9216
	ds_read_b128 v[222:225], v48 offset:9248
	ds_read_b128 v[126:129], v48 offset:9280
	ds_read_b128 v[122:125], v48 offset:9312
	ds_read_b128 v[226:229], v48 offset:13824
	ds_read_b128 v[230:233], v48 offset:13856
	ds_read_b128 v[130:133], v48 offset:13888
	ds_read_b128 v[118:121], v48 offset:13920
	s_waitcnt lgkmcnt(10)
	v_mfma_f32_32x32x16_bf16 v[32:47], v[160:163], v[94:97], v[32:47]
	s_nop 11
	v_exp_f32_e32 v32, v32
	v_exp_f32_e32 v33, v33
	v_exp_f32_e32 v34, v34
	v_exp_f32_e32 v35, v35
	v_add_f32_e32 v48, v137, v32
	v_add_f32_e32 v48, v33, v48
	v_add_f32_e32 v48, v34, v48
	v_add_f32_e32 v48, v35, v48
	v_exp_f32_e32 v36, v36
	v_exp_f32_e32 v37, v37
	v_exp_f32_e32 v38, v38
	v_exp_f32_e32 v39, v39
	v_add_f32_e32 v48, v36, v48
	v_add_f32_e32 v48, v37, v48
	v_add_f32_e32 v48, v38, v48
	v_add_f32_e32 v48, v39, v48
	v_mfma_f32_32x32x16_bf16 v[64:79], v[56:59], v[82:85], v[64:79]
	v_exp_f32_e32 v178, v40
	v_exp_f32_e32 v179, v41
	v_exp_f32_e32 v180, v42
	v_exp_f32_e32 v181, v43
	v_add_f32_e32 v40, v178, v48
	v_add_f32_e32 v40, v179, v40
	v_add_f32_e32 v40, v180, v40
	v_add_f32_e32 v40, v181, v40
	v_mfma_f32_32x32x16_bf16 v[64:79], v[60:63], v[86:89], v[64:79]
	v_exp_f32_e32 v182, v44
	s_waitcnt lgkmcnt(9)
	v_mfma_f32_32x32x16_bf16 v[64:79], v[170:173], v[90:93], v[64:79]
	v_exp_f32_e32 v170, v45
	v_exp_f32_e32 v171, v46
	v_exp_f32_e32 v172, v47
	v_add_f32_e32 v40, v182, v40
	v_add_f32_e32 v40, v170, v40
	v_add_f32_e32 v40, v171, v40
	v_add_f32_e32 v40, v172, v40
	s_waitcnt lgkmcnt(8)
	v_mfma_f32_32x32x16_bf16 v[64:79], v[174:177], v[94:97], v[64:79]
	v_cvt_pk_bf16_f32 v160, v32, v33
	v_cvt_pk_bf16_f32 v161, v34, v35
	v_cvt_pk_bf16_f32 v162, v36, v37
	v_cvt_pk_bf16_f32 v163, v38, v39
	s_nop 7
	v_exp_f32_e32 v173, v64
	v_exp_f32_e32 v174, v65
	s_waitcnt lgkmcnt(7)
	v_mfma_f32_32x32x16_bf16 v[16:31], v[218:221], v[160:163], v[16:31]
	v_exp_f32_e32 v175, v66
	v_exp_f32_e32 v176, v67
	v_add_f32_e32 v32, v173, v40
	v_add_f32_e32 v32, v174, v32
	v_add_f32_e32 v32, v175, v32
	v_add_f32_e32 v64, v176, v32
	v_exp_f32_e32 v68, v68
	v_exp_f32_e32 v69, v69
	s_waitcnt lgkmcnt(3)
	v_mfma_f32_32x32x16_bf16 v[0:15], v[226:229], v[160:163], v[0:15]
	v_exp_f32_e32 v70, v70
	v_exp_f32_e32 v71, v71
	v_add_f32_e32 v64, v68, v64
	v_add_f32_e32 v64, v69, v64
	v_add_f32_e32 v64, v70, v64
	v_add_f32_e32 v160, v71, v64
	v_cvt_pk_bf16_f32 v64, v178, v179
	v_cvt_pk_bf16_f32 v65, v180, v181
	v_cvt_pk_bf16_f32 v66, v182, v170
	v_cvt_pk_bf16_f32 v67, v171, v172
	s_nop 1
	v_mfma_f32_32x32x16_bf16 v[16:31], v[222:225], v[64:67], v[16:31]
	v_exp_f32_e32 v72, v72
	v_exp_f32_e32 v73, v73
	v_exp_f32_e32 v74, v74
	v_exp_f32_e32 v75, v75
	v_add_f32_e32 v160, v72, v160
	v_add_f32_e32 v160, v73, v160
	v_add_f32_e32 v160, v74, v160
	v_add_f32_e32 v160, v75, v160
	s_waitcnt lgkmcnt(2)
	v_mfma_f32_32x32x16_bf16 v[0:15], v[230:233], v[64:67], v[0:15]
	v_exp_f32_e32 v76, v76
	v_exp_f32_e32 v77, v77
	v_exp_f32_e32 v78, v78
	v_exp_f32_e32 v79, v79
	v_add_f32_e32 v64, v76, v160
	v_add_f32_e32 v64, v77, v64
	v_add_f32_e32 v64, v78, v64
	v_add_f32_e32 v160, v79, v64
	v_cvt_pk_bf16_f32 v64, v173, v174
	v_cvt_pk_bf16_f32 v65, v175, v176
	v_cvt_pk_bf16_f32 v66, v68, v69
	v_cvt_pk_bf16_f32 v67, v70, v71
	s_mov_b64 s[8:9], 0
	s_nop 0
	v_mfma_f32_32x32x16_bf16 v[16:31], v[126:129], v[64:67], v[16:31]
	s_waitcnt lgkmcnt(1)
	v_mfma_f32_32x32x16_bf16 v[0:15], v[130:133], v[64:67], v[0:15]
	v_cvt_pk_bf16_f32 v64, v72, v73
	v_cvt_pk_bf16_f32 v65, v74, v75
	v_cvt_pk_bf16_f32 v66, v76, v77
	v_cvt_pk_bf16_f32 v67, v78, v79
	s_nop 1
	v_mfma_f32_32x32x16_bf16 v[16:31], v[122:125], v[64:67], v[16:31]
	s_waitcnt lgkmcnt(0)
	v_mfma_f32_32x32x16_bf16 v[0:15], v[118:121], v[64:67], v[0:15]

; template <int MODE> __device__ __forceinline__ void tile_soft_gen(LAS const unsigned char* ks, LAS const unsigned char* vs, const bf16x8 (&qf)[4], f32x16 (&ot)[2], float& lsum, ...
;     const float init = MODE == 0 ? (lane_valid ? bt[BT_FAR] : -3.0e38f) : 0.f;
;     const int pr = (r & 0x13) | ((r & 4) << 1) | ((r & 8) >> 1);
;     LAS const unsigned char* kp = ks + pr * 144 + h * 16; LAS const unsigned char* vp = vs + r * 144 + h * 16;
;     bf16x8 k0[4], k1[4], v0[2][2], v1[2][2];
; #pragma unroll
;     for (int kk = 0; kk < 4; ++kk) { k0[kk] = *(LAS const bf16x8*)(kp + kk * 32); k1[kk] = *(LAS const bf16x8*)(kp + 32 * 144 + kk * 32); }
;     __builtin_amdgcn_sched_barrier(0);
;     f32x16 s0, s1;
; #pragma unroll
;     for (int i = 0; i < 16; ++i) { s0[i] = init; s1[i] = init; }
; #pragma unroll
;     for (int kk = 0; kk < 4; ++kk) s0 = MFMA32(k0[kk], qf[kk], s0);
; #pragma unroll
;     for (int mt = 0; mt < 2; ++mt)
; #pragma unroll
;         for (int j = 0; j < 2; ++j) v0[mt][j] = *(LAS const bf16x8*)(vp + 32 * mt * 144 + 32 * j);
;     __builtin_amdgcn_sched_barrier(0);
; #pragma unroll
;     for (int kk = 0; kk < 4; ++kk) s1 = MFMA32(k1[kk], qf[kk], s1);
; #pragma unroll
;     for (int mt = 0; mt < 2; ++mt)
; #pragma unroll
;         for (int j = 0; j < 2; ++j) v1[mt][j] = *(LAS const bf16x8*)(vp + 32 * mt * 144 + 64 + 32 * j);
;     soft_sub<MODE>(s0, lsum, lane_valid, dist00, dmax, bt);
;     __builtin_amdgcn_sched_barrier(0);
; #pragma unroll
;     for (int j = 0; j < 2; ++j) { const bf16x8 pf = pack_p(s0, j); ot[0] = MFMA32(v0[0][j], pf, ot[0]); ot[1] = MFMA32(v0[1][j], pf, ot[1]); }
;     soft_sub<MODE>(s1, lsum, lane_valid, dist00 - (MODE == 3 ? 512 : 32), dmax, bt);
;     __builtin_amdgcn_sched_barrier(0);
; #pragma unroll
; __device__ __forceinline__ void nsa_unit(LAS unsigned char* lds, const unsigned char* hb, const bf16_t* kc, const bf16_t* vct, const float* nsg, bf16_t* omix, int b, int g, int c, int tid) {
;     ...
;         TILE_LOOP(Kw, Vw, SEQ, kfirst, ntw, {
;             const int dist00 = t - (key0 + 8 * h);
;             if (key0 >= q0 - 128) tile_soft<1>(ks, vs, qf, ot, lsum, true, dist00, 0, bt, r, h);
;             else if (key0 == q0 - 512) tile_soft<2>(ks, vs, qf, ot, lsum, true, dist00, 512, bt, r, h);
;             else tile_soft<0>(ks, vs, qf, ot, lsum, true, dist00, 0, bt, r, h); });
.LBB0_1037:
	s_and_b32 s13, s7, 1
	s_mul_i32 s8, s13, 0x4800
	s_add_i32 s14, s8, 0x100
	v_add_u32_e32 v221, s4, v80
	v_add_u32_e32 v217, 0x200, v221
	s_mov_b64 s[8:9], -1
	s_cmp_lt_i32 s6, s5
	v_add3_u32 v220, s14, v212, v154
	v_add3_u32 v219, s14, v213, v154
	s_cbranch_scc1 .LBB0_1039
	ds_read_b128 v[32:35], v220
	ds_read_b128 v[48:51], v220 offset:32
	ds_read_b128 v[52:55], v220 offset:4608
	ds_read_b128 v[56:59], v220 offset:4640
	ds_read_b128 v[60:63], v220 offset:64
	ds_read_b128 v[170:173], v220 offset:96
	ds_read_b128 v[114:117], v220 offset:4672
	ds_read_b128 v[118:121], v220 offset:4704
	s_waitcnt lgkmcnt(7)
	v_mfma_f32_32x32x16_bf16 v[32:47], v[32:35], v[82:85], 0
	ds_read_b128 v[142:145], v219 offset:9216
	ds_read_b128 v[130:133], v219 offset:9248
	ds_read_b128 v[138:141], v219 offset:13824
	ds_read_b128 v[134:137], v219 offset:13856
	s_waitcnt lgkmcnt(10)
	v_mfma_f32_32x32x16_bf16 v[32:47], v[48:51], v[86:89], v[32:47]
	s_waitcnt lgkmcnt(7)
	v_mfma_f32_32x32x16_bf16 v[32:47], v[60:63], v[90:93], v[32:47]
	v_mfma_f32_32x32x16_bf16 v[64:79], v[52:55], v[82:85], 0
	v_med3_i32 v48, v217, s67, v192
	v_lshl_add_u32 v54, v48, 2, v211
	v_add_u32_e32 v48, 0xa2fc, v54
	v_add_u32_e32 v50, 0xa2f4, v54
	v_add_u32_e32 v52, 0xa2ec, v54
	v_add_u32_e32 v54, 0xa2e4, v54
	v_mfma_f32_32x32x16_bf16 v[64:79], v[56:59], v[86:89], v[64:79]
	v_med3_i32 v56, v217, s68, v193
	v_lshl_add_u32 v62, v56, 2, v211
	v_add_u32_e32 v56, 0xa2bc, v62
	v_add_u32_e32 v58, 0xa2b4, v62
	v_add_u32_e32 v60, 0xa2ac, v62
	v_add_u32_e32 v62, 0xa2a4, v62
	s_waitcnt lgkmcnt(5)
	v_mfma_f32_32x32x16_bf16 v[64:79], v[114:117], v[90:93], v[64:79]
	v_mfma_f32_32x32x16_bf16 v[32:47], v[170:173], v[94:97], v[32:47]
	s_waitcnt lgkmcnt(4)
	v_mfma_f32_32x32x16_bf16 v[64:79], v[118:121], v[94:97], v[64:79]
	ds_read_b128 v[122:125], v219 offset:9280
	ds_read_b128 v[118:121], v219 offset:9312
	ds_read_b128 v[126:129], v219 offset:13888
	ds_read_b128 v[114:117], v219 offset:13920
	ds_read2_b32 v[48:49], v48 offset1:1
	ds_read2_b32 v[50:51], v50 offset1:1
	ds_read2_b32 v[52:53], v52 offset1:1
	ds_read2_b32 v[54:55], v54 offset1:1
	ds_read2_b32 v[56:57], v56 offset1:1
	ds_read2_b32 v[58:59], v58 offset1:1
	ds_read2_b32 v[60:61], v60 offset1:1
	ds_read2_b32 v[62:63], v62 offset1:1
	s_waitcnt lgkmcnt(7)
	v_add_f32_e32 v32, v32, v49
	v_exp_f32_e32 v32, v32
	v_add_f32_e32 v33, v33, v48
	v_exp_f32_e32 v33, v33
	s_waitcnt lgkmcnt(6)
	v_add_f32_e32 v34, v34, v51
	v_exp_f32_e32 v34, v34
	v_add_f32_e32 v35, v35, v50
	v_exp_f32_e32 v35, v35
	s_waitcnt lgkmcnt(5)
	v_add_f32_e32 v36, v36, v53
	v_add_f32_e32 v49, v218, v32
	v_exp_f32_e32 v36, v36
	v_add_f32_e32 v37, v37, v52
	v_add_f32_e32 v48, v33, v49
	v_exp_f32_e32 v37, v37
	s_waitcnt lgkmcnt(4)
	v_add_f32_e32 v38, v38, v55
	v_add_f32_e32 v48, v34, v48
	v_exp_f32_e32 v38, v38
	v_add_f32_e32 v39, v39, v54
	v_add_f32_e32 v48, v35, v48
	v_exp_f32_e32 v39, v39
	s_waitcnt lgkmcnt(3)
	v_add_f32_e32 v40, v40, v57
	v_add_f32_e32 v48, v36, v48
	v_exp_f32_e32 v174, v40
	v_add_f32_e32 v41, v41, v56
	v_add_f32_e32 v48, v37, v48
	v_exp_f32_e32 v175, v41
	s_waitcnt lgkmcnt(2)
	v_add_f32_e32 v41, v42, v59
	v_add_f32_e32 v48, v38, v48
	v_exp_f32_e32 v176, v41
	v_add_f32_e32 v41, v43, v58
	v_add_f32_e32 v48, v39, v48
	v_exp_f32_e32 v177, v41
	s_waitcnt lgkmcnt(1)
	v_add_f32_e32 v41, v44, v61
	v_add_f32_e32 v40, v174, v48
	v_exp_f32_e32 v178, v41
	v_add_f32_e32 v41, v45, v60
	v_add_f32_e32 v40, v175, v40
	v_exp_f32_e32 v179, v41
	s_waitcnt lgkmcnt(0)
	v_add_f32_e32 v41, v46, v63
	v_add_f32_e32 v40, v176, v40
	v_exp_f32_e32 v180, v41
	v_add_f32_e32 v41, v47, v62
	v_add_f32_e32 v40, v177, v40
	v_exp_f32_e32 v181, v41
	v_add_f32_e32 v40, v178, v40
	v_add_f32_e32 v40, v179, v40
	v_add_f32_e32 v40, v180, v40
	v_add_f32_e32 v182, v181, v40
	v_cvt_pk_bf16_f32 v170, v32, v33
	v_cvt_pk_bf16_f32 v171, v34, v35
	v_cvt_pk_bf16_f32 v172, v36, v37
	v_cvt_pk_bf16_f32 v173, v38, v39
	s_nop 1
	v_mfma_f32_32x32x16_bf16 v[0:15], v[142:145], v[170:173], v[0:15]
	s_nop 0
	v_mfma_f32_32x32x16_bf16 v[16:31], v[138:141], v[170:173], v[16:31]
	v_cvt_pk_bf16_f32 v138, v174, v175
	v_cvt_pk_bf16_f32 v139, v176, v177
	v_cvt_pk_bf16_f32 v140, v178, v179
	v_cvt_pk_bf16_f32 v141, v180, v181
	s_nop 1
	v_mfma_f32_32x32x16_bf16 v[0:15], v[130:133], v[138:141], v[0:15]
	v_mfma_f32_32x32x16_bf16 v[16:31], v[134:137], v[138:141], v[16:31]
	v_add_u32_e32 v138, 0x1e0, v221
	v_med3_i32 v130, v138, s67, v192
	v_lshl_add_u32 v136, v130, 2, v211
	v_add_u32_e32 v130, 0xa2fc, v136
	ds_read2_b32 v[130:131], v130 offset1:1
	v_add_u32_e32 v132, 0xa2f4, v136
	ds_read2_b32 v[132:133], v132 offset1:1
	v_add_u32_e32 v134, 0xa2ec, v136
	ds_read2_b32 v[134:135], v134 offset1:1
	v_add_u32_e32 v136, 0xa2e4, v136
	ds_read2_b32 v[136:137], v136 offset1:1
	v_med3_i32 v138, v138, s68, v193
	s_waitcnt lgkmcnt(3)
	v_add_f32_e32 v64, v64, v131
	v_lshl_add_u32 v144, v138, 2, v211
	v_exp_f32_e32 v64, v64
	v_add_f32_e32 v65, v65, v130
	v_add_u32_e32 v138, 0xa2bc, v144
	v_exp_f32_e32 v65, v65
	s_waitcnt lgkmcnt(2)
	v_add_f32_e32 v66, v66, v133
	ds_read2_b32 v[138:139], v138 offset1:1
	v_exp_f32_e32 v66, v66
	v_add_f32_e32 v67, v67, v132
	v_add_u32_e32 v140, 0xa2b4, v144
	v_exp_f32_e32 v67, v67
	s_waitcnt lgkmcnt(2)
	v_add_f32_e32 v68, v68, v135
	ds_read2_b32 v[140:141], v140 offset1:1
	v_add_f32_e32 v131, v182, v64
	v_exp_f32_e32 v68, v68
	v_add_f32_e32 v69, v69, v134
	v_add_u32_e32 v142, 0xa2ac, v144
	v_add_f32_e32 v130, v65, v131
	v_exp_f32_e32 v69, v69
	s_waitcnt lgkmcnt(2)
	v_add_f32_e32 v70, v70, v137
	ds_read2_b32 v[142:143], v142 offset1:1
	v_add_u32_e32 v144, 0xa2a4, v144
	v_add_f32_e32 v130, v66, v130
	v_exp_f32_e32 v70, v70
	v_add_f32_e32 v71, v71, v136
	ds_read2_b32 v[144:145], v144 offset1:1
	v_add_f32_e32 v130, v67, v130
	v_exp_f32_e32 v71, v71
	s_waitcnt lgkmcnt(3)
; template <int MODE> __device__ __forceinline__ void tile_soft_gen(LAS const unsigned char* ks, LAS const unsigned char* vs, const bf16x8 (&qf)[4], f32x16 (&ot)[2], float& lsum, ...
;     const float init = MODE == 0 ? (lane_valid ? bt[BT_FAR] : -3.0e38f) : 0.f;
;     const int pr = (r & 0x13) | ((r & 4) << 1) | ((r & 8) >> 1);
;     LAS const unsigned char* kp = ks + pr * 144 + h * 16; LAS const unsigned char* vp = vs + r * 144 + h * 16;
;     bf16x8 k0[4], k1[4], v0[2][2], v1[2][2];
; #pragma unroll
;     for (int kk = 0; kk < 4; ++kk) { k0[kk] = *(LAS const bf16x8*)(kp + kk * 32); k1[kk] = *(LAS const bf16x8*)(kp + 32 * 144 + kk * 32); }
;     __builtin_amdgcn_sched_barrier(0);
;     f32x16 s0, s1;
; #pragma unroll
;     for (int i = 0; i < 16; ++i) { s0[i] = init; s1[i] = init; }
; #pragma unroll
;     for (int kk = 0; kk < 4; ++kk) s0 = MFMA32(k0[kk], qf[kk], s0);
; #pragma unroll
;     for (int mt = 0; mt < 2; ++mt)
; #pragma unroll
;         for (int j = 0; j < 2; ++j) v0[mt][j] = *(LAS const bf16x8*)(vp + 32 * mt * 144 + 32 * j);
;     __builtin_amdgcn_sched_barrier(0);
; #pragma unroll
;     for (int kk = 0; kk < 4; ++kk) s1 = MFMA32(k1[kk], qf[kk], s1);
; #pragma unroll
;     for (int mt = 0; mt < 2; ++mt)
; #pragma unroll
;         for (int j = 0; j < 2; ++j) v1[mt][j] = *(LAS const bf16x8*)(vp + 32 * mt * 144 + 64 + 32 * j);
;     soft_sub<MODE>(s0, lsum, lane_valid, dist00, dmax, bt);
;     __builtin_amdgcn_sched_barrier(0);
; #pragma unroll
;     for (int j = 0; j < 2; ++j) { const bf16x8 pf = pack_p(s0, j); ot[0] = MFMA32(v0[0][j], pf, ot[0]); ot[1] = MFMA32(v0[1][j], pf, ot[1]); }
;     soft_sub<MODE>(s1, lsum, lane_valid, dist00 - (MODE == 3 ? 512 : 32), dmax, bt);
;     __builtin_amdgcn_sched_barrier(0);
; #pragma unroll
; __device__ __forceinline__ void nsa_unit(LAS unsigned char* lds, const unsigned char* hb, const bf16_t* kc, const bf16_t* vct, const float* nsg, bf16_t* omix, int b, int g, int c, int tid) {
;     ...
;         TILE_LOOP(Kw, Vw, SEQ, kfirst, ntw, {
;             const int dist00 = t - (key0 + 8 * h);
;             if (key0 >= q0 - 128) tile_soft<1>(ks, vs, qf, ot, lsum, true, dist00, 0, bt, r, h);
;             else if (key0 == q0 - 512) tile_soft<2>(ks, vs, qf, ot, lsum, true, dist00, 512, bt, r, h);
;             else tile_soft<0>(ks, vs, qf, ot, lsum, true, dist00, 0, bt, r, h); });
	v_add_f32_e32 v72, v72, v139
	v_add_f32_e32 v130, v68, v130
	v_exp_f32_e32 v72, v72
	v_add_f32_e32 v73, v73, v138
	v_add_f32_e32 v130, v69, v130
	v_exp_f32_e32 v73, v73
	s_waitcnt lgkmcnt(2)
	v_add_f32_e32 v74, v74, v141
	v_add_f32_e32 v130, v70, v130
	v_exp_f32_e32 v74, v74
	v_add_f32_e32 v75, v75, v140
	v_add_f32_e32 v130, v71, v130
	v_exp_f32_e32 v75, v75
	s_waitcnt lgkmcnt(1)
	v_add_f32_e32 v76, v76, v143
	v_add_f32_e32 v130, v72, v130
	v_exp_f32_e32 v76, v76
	v_add_f32_e32 v77, v77, v142
	v_add_f32_e32 v130, v73, v130
	v_exp_f32_e32 v77, v77
	s_waitcnt lgkmcnt(0)
	v_add_f32_e32 v78, v78, v145
	v_add_f32_e32 v130, v74, v130
	v_exp_f32_e32 v78, v78
	v_add_f32_e32 v79, v79, v144
	v_add_f32_e32 v130, v75, v130
	v_exp_f32_e32 v79, v79
	v_add_f32_e32 v130, v76, v130
	v_add_f32_e32 v130, v77, v130
	v_add_f32_e32 v130, v78, v130
	v_add_f32_e32 v130, v79, v130
	v_cvt_pk_bf16_f32 v64, v64, v65
	v_cvt_pk_bf16_f32 v65, v66, v67
	v_cvt_pk_bf16_f32 v66, v68, v69
	v_cvt_pk_bf16_f32 v67, v70, v71
	s_mov_b64 s[8:9], 0
	s_nop 0
	v_mfma_f32_32x32x16_bf16 v[0:15], v[122:125], v[64:67], v[0:15]
	v_mfma_f32_32x32x16_bf16 v[16:31], v[126:129], v[64:67], v[16:31]
	v_cvt_pk_bf16_f32 v64, v72, v73
	v_cvt_pk_bf16_f32 v65, v74, v75
	v_cvt_pk_bf16_f32 v66, v76, v77
	v_cvt_pk_bf16_f32 v67, v78, v79
	s_nop 1
	v_mfma_f32_32x32x16_bf16 v[0:15], v[118:121], v[64:67], v[0:15]
	v_mfma_f32_32x32x16_bf16 v[16:31], v[114:117], v[64:67], v[16:31]
.LBB0_1039:
	s_andn2_b64 vcc, exec, s[8:9]
	s_cbranch_vccnz .LBB0_1043
	s_cmp_lg_u32 s4, 0
	s_cbranch_scc0 .LBB0_1047
	v_mov_b32_e32 v64, v234
	s_nop 5
	ds_read_b128 v[48:51], v220
	ds_read_b128 v[52:55], v220 offset:32
	ds_read_b128 v[56:59], v220 offset:64
	ds_read_b128 v[60:63], v220 offset:4640
	ds_read_b128 v[130:133], v220 offset:4672
	ds_read_b128 v[134:137], v220 offset:4608
	ds_read_b128 v[138:141], v220 offset:96
	ds_read_b128 v[142:145], v220 offset:4704
	s_waitcnt lgkmcnt(8)
	v_mov_b32_e32 v65, v64
	v_mov_b32_e32 v66, v64
	v_mov_b32_e32 v67, v64
	v_mov_b32_e32 v68, v64
	v_mov_b32_e32 v69, v64
	v_mov_b32_e32 v70, v64
	v_mov_b32_e32 v71, v64
	v_mov_b32_e32 v72, v64
	v_mov_b32_e32 v73, v64
	v_mov_b32_e32 v74, v64
	v_mov_b32_e32 v75, v64
	v_mov_b32_e32 v76, v64
	v_mov_b32_e32 v77, v64
	v_mov_b32_e32 v78, v64
	v_mov_b32_e32 v79, v64
	ds_read_b128 v[170:173], v219 offset:9216
	ds_read_b128 v[174:177], v219 offset:9248
	ds_read_b128 v[122:125], v219 offset:9280
	ds_read_b128 v[118:121], v219 offset:9312
	ds_read_b128 v[222:225], v219 offset:13824
	ds_read_b128 v[226:229], v219 offset:13856
	ds_read_b128 v[126:129], v219 offset:13888
	ds_read_b128 v[114:117], v219 offset:13920
	s_waitcnt lgkmcnt(14)
	v_mfma_f32_32x32x16_bf16 v[32:47], v[48:51], v[82:85], v[64:79]
	v_mfma_f32_32x32x16_bf16 v[32:47], v[52:55], v[86:89], v[32:47]
	s_waitcnt lgkmcnt(13)
	v_mfma_f32_32x32x16_bf16 v[32:47], v[56:59], v[90:93], v[32:47]
	s_waitcnt lgkmcnt(9)
	v_mfma_f32_32x32x16_bf16 v[32:47], v[138:141], v[94:97], v[32:47]
	s_nop 11
	v_exp_f32_e32 v32, v32
	v_exp_f32_e32 v33, v33
	v_exp_f32_e32 v34, v34
	v_exp_f32_e32 v35, v35
	v_add_f32_e32 v48, v218, v32
	v_add_f32_e32 v48, v33, v48
	v_add_f32_e32 v48, v34, v48
	v_add_f32_e32 v48, v35, v48
	v_exp_f32_e32 v36, v36
	v_exp_f32_e32 v37, v37
	v_exp_f32_e32 v38, v38
	v_exp_f32_e32 v39, v39
	v_add_f32_e32 v48, v36, v48
	v_add_f32_e32 v48, v37, v48
	v_add_f32_e32 v48, v38, v48
	v_add_f32_e32 v48, v39, v48
	v_mfma_f32_32x32x16_bf16 v[64:79], v[134:137], v[82:85], v[64:79]
	v_exp_f32_e32 v134, v40
	v_exp_f32_e32 v135, v41
	v_exp_f32_e32 v136, v42
	v_exp_f32_e32 v137, v43
	v_add_f32_e32 v40, v134, v48
	v_add_f32_e32 v40, v135, v40
	v_add_f32_e32 v40, v136, v40
	v_add_f32_e32 v40, v137, v40
	v_mfma_f32_32x32x16_bf16 v[64:79], v[60:63], v[86:89], v[64:79]
	v_exp_f32_e32 v138, v44
	v_mfma_f32_32x32x16_bf16 v[64:79], v[130:133], v[90:93], v[64:79]
	v_exp_f32_e32 v139, v45
	v_exp_f32_e32 v140, v46
	v_exp_f32_e32 v141, v47
	v_add_f32_e32 v40, v138, v40
	v_add_f32_e32 v40, v139, v40
	v_add_f32_e32 v40, v140, v40
	v_add_f32_e32 v40, v141, v40
	s_waitcnt lgkmcnt(8)
	v_mfma_f32_32x32x16_bf16 v[64:79], v[142:145], v[94:97], v[64:79]
	v_cvt_pk_bf16_f32 v130, v32, v33
	v_cvt_pk_bf16_f32 v131, v34, v35
	v_cvt_pk_bf16_f32 v132, v36, v37
	v_cvt_pk_bf16_f32 v133, v38, v39
	s_nop 7
	v_exp_f32_e32 v142, v64
	v_exp_f32_e32 v143, v65
	s_waitcnt lgkmcnt(7)
	v_mfma_f32_32x32x16_bf16 v[0:15], v[170:173], v[130:133], v[0:15]
	v_exp_f32_e32 v144, v66
	v_exp_f32_e32 v145, v67
	v_add_f32_e32 v32, v142, v40
	v_add_f32_e32 v32, v143, v32
	v_add_f32_e32 v32, v144, v32
	v_add_f32_e32 v64, v145, v32
	v_exp_f32_e32 v68, v68
	v_exp_f32_e32 v69, v69
	s_waitcnt lgkmcnt(3)
	v_mfma_f32_32x32x16_bf16 v[16:31], v[222:225], v[130:133], v[16:31]
	v_exp_f32_e32 v70, v70
	v_exp_f32_e32 v71, v71
	v_add_f32_e32 v64, v68, v64
	v_add_f32_e32 v64, v69, v64
	v_add_f32_e32 v64, v70, v64
	v_add_f32_e32 v130, v71, v64
	v_cvt_pk_bf16_f32 v64, v134, v135
	v_cvt_pk_bf16_f32 v65, v136, v137
	v_cvt_pk_bf16_f32 v66, v138, v139
	v_cvt_pk_bf16_f32 v67, v140, v141
	s_nop 1
	v_mfma_f32_32x32x16_bf16 v[0:15], v[174:177], v[64:67], v[0:15]
	v_exp_f32_e32 v72, v72
	v_exp_f32_e32 v73, v73
	v_exp_f32_e32 v74, v74
	v_exp_f32_e32 v75, v75
	v_add_f32_e32 v130, v72, v130
	v_add_f32_e32 v130, v73, v130
	v_add_f32_e32 v130, v74, v130
	v_add_f32_e32 v130, v75, v130
	s_waitcnt lgkmcnt(2)
	v_mfma_f32_32x32x16_bf16 v[16:31], v[226:229], v[64:67], v[16:31]
	v_exp_f32_e32 v76, v76
	v_exp_f32_e32 v77, v77
	v_exp_f32_e32 v78, v78
	v_exp_f32_e32 v79, v79
	v_add_f32_e32 v64, v76, v130
	v_add_f32_e32 v64, v77, v64
	v_add_f32_e32 v64, v78, v64
	v_add_f32_e32 v130, v79, v64
	v_cvt_pk_bf16_f32 v64, v142, v143
	v_cvt_pk_bf16_f32 v65, v144, v145
	v_cvt_pk_bf16_f32 v66, v68, v69
	v_cvt_pk_bf16_f32 v67, v70, v71
	s_nop 1
	v_mfma_f32_32x32x16_bf16 v[0:15], v[122:125], v[64:67], v[0:15]
	s_waitcnt lgkmcnt(1)
	v_mfma_f32_32x32x16_bf16 v[16:31], v[126:129], v[64:67], v[16:31]
	v_cvt_pk_bf16_f32 v64, v72, v73
	v_cvt_pk_bf16_f32 v65, v74, v75
	v_cvt_pk_bf16_f32 v66, v76, v77
	v_cvt_pk_bf16_f32 v67, v78, v79
	s_nop 1
	v_mfma_f32_32x32x16_bf16 v[0:15], v[118:121], v[64:67], v[0:15]
	s_waitcnt lgkmcnt(0)
	v_mfma_f32_32x32x16_bf16 v[16:31], v[114:117], v[64:67], v[16:31]
	s_cbranch_execnz .LBB0_1043

; __device__ __forceinline__ float bflo(unsigned w) { return __uint_as_float(w << 16); }
; __device__ __forceinline__ float bfhi(unsigned w) { return __uint_as_float(w & 0xffff0000u); }
; __device__ __forceinline__ void nsa_unit(LAS unsigned char* lds, const unsigned char* hb, const bf16_t* kc, const bf16_t* vct, const float* nsg, bf16_t* omix, int b, int g, int c, int tid) {
;     ...
;         TILE_LOOP(Kw, Vw, SEQ, kfirst, ntw, {
;             const int dist00 = t - (key0 + 8 * h);
;             if (key0 >= q0 - 128) tile_soft<1>(ks, vs, qf, ot, lsum, true, dist00, 0, bt, r, h);
;             else if (key0 == q0 - 512) tile_soft<2>(ks, vs, qf, ot, lsum, true, dist00, 512, bt, r, h);
;             else tile_soft<0>(ks, vs, qf, ot, lsum, true, dist00, 0, bt, r, h); });
;         const float l = lsum + __shfl_xor(lsum, 32); const float gw = gate[16] / fmaxf(l, 1e-30f);
; #pragma unroll
;         for (int i = 0; i < 8; ++i) { const unsigned a0 = oal[i * 64], a1 = oal[(8 + i) * 64];
;             ot[0][2 * i] = bflo(a0) + ot[0][2 * i] * gw; ot[0][2 * i + 1] = bfhi(a0) + ot[0][2 * i + 1] * gw; ot[1][2 * i] = bflo(a1) + ot[1][2 * i] * gw; ot[1][2 * i + 1] = bfhi(a1) + ot[1][2 * i + 1] * gw; } }
;     store_ot(omix + ((size_t)b * SEQ + t) * DM + 512 + hq * 64, ot, h);
.LBB0_1043:
	s_cmp_ge_i32 s7, s10
	s_cbranch_scc1 .LBB0_1045
	s_xor_b32 s8, s13, 1
	s_mulk_i32 s8, 0x4800
	v_add_u32_e32 v32, s8, v155
	s_waitcnt vmcnt(1)
	ds_write_b128 v32, v[98:101]
	s_waitcnt vmcnt(0)
	ds_write_b128 v32, v[102:105] offset:9216
.LBB0_1045:
	s_add_i32 s7, s7, 1
	s_add_i32 s6, s6, 64
	s_sub_i32 s4, s4, 64
	s_cmp_lg_u32 s12, s7
	v_lshl_add_u64 v[162:163], v[162:163], 0, s[82:83]
	s_waitcnt lgkmcnt(0)
	s_barrier
	s_cbranch_scc0 .Lp4_exit
	s_waitcnt vmcnt(0)
	v_mov_b64_e32 v[102:103], v[106:107]
	v_mov_b64_e32 v[98:99], v[110:111]
	v_mov_b32_e32 v218, v130
	v_mov_b64_e32 v[104:105], v[108:109]
	v_mov_b64_e32 v[100:101], v[112:113]
	s_cmp_gt_i32 s7, s11
	s_cbranch_scc0 .LBB0_1036
	s_branch .LBB0_1037
.Lp4_exit:
	s_nop 7
	v_mov_b32_e32 v48, v0
	v_mov_b32_e32 v49, v1
	v_mov_b32_e32 v50, v2
	v_mov_b32_e32 v51, v3
	v_mov_b32_e32 v52, v4
	v_mov_b32_e32 v53, v5
	v_mov_b32_e32 v54, v6
	v_mov_b32_e32 v55, v7
	v_mov_b32_e32 v56, v8
	v_mov_b32_e32 v57, v9
	v_mov_b32_e32 v58, v10
	v_mov_b32_e32 v59, v11
	v_mov_b32_e32 v60, v12
	v_mov_b32_e32 v61, v13
	v_mov_b32_e32 v62, v14
	v_mov_b32_e32 v63, v15
	v_mov_b32_e32 v32, v16
	v_mov_b32_e32 v33, v17
	v_mov_b32_e32 v34, v18
	v_mov_b32_e32 v35, v19
	v_mov_b32_e32 v36, v20
	v_mov_b32_e32 v37, v21
	v_mov_b32_e32 v38, v22
	v_mov_b32_e32 v39, v23
	v_mov_b32_e32 v40, v24
	v_mov_b32_e32 v41, v25
	v_mov_b32_e32 v42, v26
	v_mov_b32_e32 v43, v27
	v_mov_b32_e32 v44, v28
	v_mov_b32_e32 v45, v29
	v_mov_b32_e32 v46, v30
	v_mov_b32_e32 v47, v31
	s_branch .LBB0_806

; __global__ void __launch_bounds__(512, 2) hybrid_fwd(Params P) {
;     ...
;         { PHASE_BEGIN
;             for (int it = bx; it < 256; it += G)
;                 for (int i = 0; i < 4; ++i) { int tidu = tid; asm volatile("" : "+v"(tidu));
;                     branch_tile(lds, (const bf16_t*)(ws + WS_H), (const bf16_t*)(ws + WS_WBR), (const bf16_t*)(ws + WS_A), (bf16_t*)(ws + WS_B), it >> 1, 4 * (it & 1) + i, tidu); }
.LBB0_1085:
	s_nop 0
	s_nop 0
	s_nop 0
	s_nop 0
	s_nop 0
	s_nop 0
	s_nop 0
	s_nop 0
	s_nop 0
	s_nop 0
	s_nop 0
	s_nop 0
	s_nop 0
	s_nop 0
	s_or_b64 exec, exec, s[4:5]
	s_mov_b32 s4, s34
	s_barrier
	s_mov_b64 s[4:5], s[58:59]
	s_mov_b32 s16, s69
	s_mov_b32 s17, s2
	v_mov_b32_e32 v138, v146
	s_cmpk_gt_i32 s17, 0xff
	s_cbranch_scc1 .LBB0_1096
	s_add_u32 s18, s4, 0x3100000
	s_addc_u32 s19, s5, 0
	s_add_u32 s20, s4, 0xd00000
	s_addc_u32 s21, s5, 0
	s_add_u32 s6, s4, 0x7100000
	s_addc_u32 s7, s5, 0
	s_add_u32 s8, s4, 0x13100000
	s_addc_u32 s9, s5, 0
	s_branch .LBB0_1088
